# prompt attention unit prologue: the qb+1 selection-mask loads are issued together and waited for once (was load / vmcnt(0) / invert / ds_write, one after the other)
# speedup vs baseline: 1.0110x; 1.0110x over previous
.LBB0_1886:
	s_and_b64 s[4:5], s[2:3], exec
	s_cselect_b32 s8, s39, s33
	v_readfirstlane_b32 s7, v0
	s_lshl_b32 s4, s8, 3
	s_lshr_b32 s52, s7, 6
	s_or_b32 s4, s4, s46
	s_lshl_b32 s61, s52, 13
	s_add_i32 s4, s4, s52
	s_add_i32 s6, s61, 0
	s_ashr_i32 s5, s4, 31
	s_add_i32 s6, s6, 0x15000
	s_lshl_b64 s[4:5], s[4:5], 13
	s_add_u32 s4, s44, s4
	s_addc_u32 s5, s45, s5
	global_load_dwordx4 v[36:39], v204, s[4:5]
	s_cmp_lg_u32 s8, 0
	v_lshl_add_u64 v[4:5], s[4:5], 0, v[204:205]
	s_cselect_b64 s[42:43], -1, 0
	s_cmp_lt_u32 s8, 1
	s_cbranch_scc1 .Lml_issued
	global_load_dwordx4 v[40:43], v[4:5], off offset:1024
	s_cmp_lt_u32 s8, 2
	s_cbranch_scc1 .Lml_issued
	global_load_dwordx4 v[44:47], v[4:5], off offset:2048
	s_cmp_lt_u32 s8, 3
	s_cbranch_scc1 .Lml_issued
	global_load_dwordx4 v[48:51], v[4:5], off offset:3072
	s_cmp_lt_u32 s8, 4
	s_cbranch_scc1 .Lml_issued
	global_load_dwordx4 v[52:55], v245, s[4:5]
	s_cmp_lt_u32 s8, 5
	s_cbranch_scc1 .Lml_issued
	global_load_dwordx4 v[56:59], v246, s[4:5]
	s_cmp_lt_u32 s8, 6
	s_cbranch_scc1 .Lml_issued
	global_load_dwordx4 v[60:63], v247, s[4:5]
	s_cmp_lt_u32 s8, 7
	s_cbranch_scc1 .Lml_issued
	global_load_dwordx4 v[64:67], v248, s[4:5]
.Lml_issued:
	s_waitcnt vmcnt(0)
	v_not_b32_e32 v36, v36
	v_not_b32_e32 v37, v37
	v_not_b32_e32 v38, v38
	v_not_b32_e32 v39, v39
	v_add_u32_e32 v2, s6, v1
	ds_write_b128 v2, v[36:39]
	s_cmp_lt_u32 s8, 1
	s_cbranch_scc1 .LBB0_1900
	v_not_b32_e32 v40, v40
	v_not_b32_e32 v41, v41
	v_not_b32_e32 v42, v42
	v_not_b32_e32 v43, v43
	v_add_u32_e32 v2, s6, v228
	ds_write_b128 v2, v[40:43]
	s_cmp_lt_u32 s8, 2
	s_cbranch_scc1 .LBB0_1900
	v_not_b32_e32 v44, v44
	v_not_b32_e32 v45, v45
	v_not_b32_e32 v46, v46
	v_not_b32_e32 v47, v47
	v_add_u32_e32 v2, s6, v229
	ds_write_b128 v2, v[44:47]
	s_cmp_lt_u32 s8, 3
	s_cbranch_scc1 .LBB0_1900
	v_not_b32_e32 v48, v48
	v_not_b32_e32 v49, v49
	v_not_b32_e32 v50, v50
	v_not_b32_e32 v51, v51
	v_add_u32_e32 v2, s6, v230
	ds_write_b128 v2, v[48:51]
	s_cmp_lt_u32 s8, 4
	s_cbranch_scc1 .LBB0_1900
	v_not_b32_e32 v52, v52
	v_not_b32_e32 v53, v53
	v_not_b32_e32 v54, v54
	v_not_b32_e32 v55, v55
	v_add_u32_e32 v2, s6, v231
	ds_write_b128 v2, v[52:55]
	s_cmp_lt_u32 s8, 5
	s_cbranch_scc1 .LBB0_1900
	v_not_b32_e32 v56, v56
	v_not_b32_e32 v57, v57
	v_not_b32_e32 v58, v58
	v_not_b32_e32 v59, v59
	v_add_u32_e32 v2, s6, v232
	ds_write_b128 v2, v[56:59]
	s_cmp_lt_u32 s8, 6
	s_cbranch_scc1 .LBB0_1900
	v_not_b32_e32 v60, v60
	v_not_b32_e32 v61, v61
	v_not_b32_e32 v62, v62
	v_not_b32_e32 v63, v63
	v_add_u32_e32 v2, s6, v233
	ds_write_b128 v2, v[60:63]
	s_cmp_lt_u32 s8, 7
	s_cbranch_scc1 .LBB0_1900
	v_not_b32_e32 v64, v64
	v_not_b32_e32 v65, v65
	v_not_b32_e32 v66, v66
	v_not_b32_e32 v67, v67
	v_add_u32_e32 v2, s6, v234
	ds_write_b128 v2, v[64:67]
